# LRU pass 1: the 16 extra items per head go one per block (wave (bx>>4)&7, keeps item&7 == wave), so no block has all 8 waves running a 9th item
# baseline (speedup 1.0000x reference)
; #define LAS __attribute__((address_space(3)))
; #define LDS_WAIT() asm volatile("s_waitcnt lgkmcnt(0)" ::: "memory")
; template <int PASS>
; __device__ __forceinline__ void lru_item(Frame& F, const LAS bf16* lw, const LAS float* prm, const LAS float* cwl, LAS float* xs, LAS unsigned char* pf, int head, int item, int nitem) {
;     ...
;     u32x4 vw[4][4];
; #pragma unroll
;     for (int k = 0; k < 4; ++k) {
;         const int rr = r - 1 + k; const bool ok = (rr >= 0) && (rr < 256);
;         const int row = t + k;
; #pragma unroll
;         for (int ks = 0; ks < 4; ++ks) { u32x4 w = *(const LAS u32x4*)(pf + row * 128 + (((2 * ks + hh) ^ ((row >> 1) & 7)) * 16)); if (!ok) w = (u32x4){0u, 0u, 0u, 0u}; vw[k][ks] = w; }
;     }
;     LDS_WAIT(); asm volatile("" ::: "memory");
; template <int PASS>
; __device__ __forceinline__ void lru_phase(Frame& F, const Params& p) {
;     ...
;         if (PASS == 2) while (it < nitems && ((it >> 3) % 65) == 64) it += NWG;
;         if (it < nitems) { int ln = F.lane; asm volatile("" : "+v"(ln)); lru_prefetch(F.ws, pf, ln, head, it); }
;         while (it < nitems) {
;             int nx = it + NWG;
;             if (PASS == 2) while (nx < nitems && ((nx >> 3) % 65) == 64) nx += NWG;
;             lru_item<PASS>(F, lw, prm, cwl, xs, pf, head, it, nx < nitems ? nx : -1);
;             it = nx;
.LBB0_694:
	v_mov_b32_e32 v111, v108
	s_waitcnt vmcnt(4)
	s_add_i32 s80, s62, s45
	s_cmpk_lt_i32 s80, 0x400
	s_cbranch_scc1 .Lmy_nx_ok
	s_movk_i32 s80, 0x7fff
	s_cmpk_ge_i32 s62, 0x400
	s_cbranch_scc1 .Lmy_nx_ok
	s_lshr_b32 s99, s2, 4
	s_and_b32 s99, s99, 7
	s_cmp_lg_u32 s95, s99
	s_cbranch_scc1 .Lmy_nx_ok
	s_lshr_b32 s80, s2, 4
	s_addk_i32 s80, 0x400
.Lmy_nx_ok:
	v_and_b32_e32 v110, 31, v111
	v_ashrrev_i32_e32 v112, 5, v111
	v_lshrrev_b32_e32 v1, 1, v111
	v_lshl_add_u32 v0, v110, 7, s46
	v_bitop3_b32 v2, v1, v112, 7 bitop3:0x6c
	v_add_u32_e32 v32, 2, v112
	v_lshl_add_u32 v2, v2, 4, v0
	v_bitop3_b32 v3, v32, v1, 7 bitop3:0x78
	v_add_u32_e32 v33, 4, v112
	v_add_u32_e32 v34, 6, v112
	v_lshl_add_u32 v3, v3, 4, v0
	ds_read_b128 v[20:23], v2
	s_waitcnt lgkmcnt(0)
	ds_read_b128 v[8:11], v3
	v_bitop3_b32 v2, v33, v1, 7 bitop3:0x78
	v_bitop3_b32 v1, v34, v1, 7 bitop3:0x78
	v_lshl_add_u32 v2, v2, 4, v0
	v_lshl_add_u32 v0, v1, 4, v0
	ds_read_b128 v[24:27], v2
	ds_read_b128 v[16:19], v0
	v_add_u32_e32 v0, 1, v110
	v_lshl_add_u32 v1, v0, 7, s46
	v_lshrrev_b32_e32 v0, 1, v0
	v_bitop3_b32 v2, v0, v112, 7 bitop3:0x6c
	v_add_u32_e32 v35, 2, v110
	v_lshl_add_u32 v2, v2, 4, v1
	v_bitop3_b32 v3, v0, v32, 7 bitop3:0x6c
	v_lshl_add_u32 v36, v35, 7, s46
	v_lshrrev_b32_e32 v35, 1, v35
	v_lshl_add_u32 v3, v3, 4, v1
	ds_read_b128 v[28:31], v2
	ds_read_b128 v[12:15], v3
	v_bitop3_b32 v2, v0, v33, 7 bitop3:0x6c
	v_bitop3_b32 v0, v0, v34, 7 bitop3:0x6c
	v_bitop3_b32 v37, v35, v112, 7 bitop3:0x6c
	v_lshl_add_u32 v2, v2, 4, v1
	v_lshl_add_u32 v0, v0, 4, v1
	v_lshl_add_u32 v37, v37, 4, v36
	v_bitop3_b32 v38, v35, v32, 7 bitop3:0x6c
	ds_read_b128 v[4:7], v2
	ds_read_b128 v[0:3], v0
	v_lshl_add_u32 v38, v38, 4, v36
	ds_read_b128 v[60:63], v37
	ds_read_b128 v[44:47], v38
	v_bitop3_b32 v37, v35, v33, 7 bitop3:0x6c
	v_bitop3_b32 v35, v35, v34, 7 bitop3:0x6c
	v_lshl_add_u32 v37, v37, 4, v36
	v_lshl_add_u32 v35, v35, 4, v36
	ds_read_b128 v[52:55], v37
	ds_read_b128 v[36:39], v35
	v_add_u32_e32 v35, 3, v110
	v_lshl_add_u32 v48, v35, 7, s46
	v_lshrrev_b32_e32 v35, 1, v35
	v_bitop3_b32 v40, v35, v112, 7 bitop3:0x6c
	v_bitop3_b32 v32, v35, v32, 7 bitop3:0x6c
	v_lshl_add_u32 v40, v40, 4, v48
	v_lshl_add_u32 v32, v32, 4, v48
	ds_read_b128 v[56:59], v40
	ds_read_b128 v[40:43], v32
	v_bitop3_b32 v32, v35, v33, 7 bitop3:0x6c
	v_bitop3_b32 v33, v35, v34, 7 bitop3:0x6c
	v_lshl_add_u32 v32, v32, 4, v48
	v_lshl_add_u32 v33, v33, 4, v48
	ds_read_b128 v[48:51], v32
	ds_read_b128 v[32:35], v33
	s_cmpk_gt_i32 s80, 0x40f
	s_waitcnt lgkmcnt(0)
	s_cselect_b64 s[6:7], -1, 0
	s_cmpk_lt_i32 s80, 0x410
	s_cselect_b32 s12, s80, -1
	s_cmp_lt_i32 s12, 0
	s_cbranch_scc1 .LBB0_702
	s_lshr_b32 s4, s12, 3
	s_mul_hi_u32 s8, s4, 0x3f03f04
	s_mulk_i32 s8, 0x41
	s_sub_i32 s4, s4, s8
	s_mul_hi_u32 s8, s12, 0xfc0fc0fd
	s_lshr_b32 s10, s8, 9
	s_cmp_lt_u32 s4, 64
	s_cselect_b64 s[8:9], -1, 0
	s_lshl_b32 s13, s10, 8
	s_lshl_b32 s10, s10, 14
	s_or_b32 s4, s10, s4
	s_and_b64 s[10:11], s[8:9], exec
	s_cselect_b32 s10, s31, 0x3e300000
	s_cselect_b32 s4, s4, s13
	s_add_u32 s13, s56, s10
	s_addc_u32 s63, s57, 0
	s_lshl_b64 s[10:11], s[4:5], 11
	s_add_u32 s4, s13, s10
	s_addc_u32 s11, s63, s11
	s_add_u32 s10, s4, s34
	s_addc_u32 s11, s11, 0
	s_lshl_b32 s4, s12, 5
	s_and_b32 s4, s4, 0xe0
	v_lshrrev_b32_e32 v64, 4, v111
	s_add_i32 s4, s4, -1
	v_cmp_gt_i32_e32 vcc, s35, v111
	v_xor_b32_e32 v64, v64, v111
	s_and_saveexec_b64 s[12:13], vcc
	s_cbranch_execnz .LBB0_710
	s_or_b64 exec, exec, s[12:13]
	v_cmp_gt_i32_e32 vcc, s36, v111
	s_and_saveexec_b64 s[12:13], vcc
	s_cbranch_execnz .LBB0_711
